# v047 plus inter-chunk scan with all 32 chunk loads in flight (counted vmcnt, cd via one load + v_readlane) and plain SLOC stores in passA
# baseline (speedup 1.0000x reference)
.LBB0_661:
	s_or_b64 exec, exec, s[12:13]
	v_and_b32_e32 v18, 15, v74
	s_lshl_b32 s6, s86, 4
	v_and_b32_e32 v1, 48, v74
	v_or_b32_e32 v0, s6, v18
	v_add_u32_e32 v16, 0, v1
	v_mad_u64_u32 v[0:1], s[8:9], v0, s92, v[16:17]
	v_mad_u32_u24 v17, v18, s92, v16
	s_waitcnt lgkmcnt(0)
	s_barrier
	ds_read_b128 v[12:15], v0 offset:54272
	ds_read_b128 v[8:11], v0 offset:54336
	ds_read_b128 v[4:7], v0 offset:54400
	ds_read_b128 v[0:3], v0 offset:54464
	ds_read_b128 v[22:25], v17 offset:2048
	ds_read_b128 v[26:29], v17 offset:2112
	ds_read_b128 v[30:33], v17 offset:2176
	ds_read_b128 v[34:37], v17 offset:2240
	s_waitcnt lgkmcnt(3)
	v_mfma_f32_16x16x32_bf16 v[22:25], v[22:25], v[12:15], 0
	s_lshl_b32 s2, s2, 5
	s_or_b32 s1, s2, s1
	s_mul_i32 s1, s1, 12
	s_waitcnt lgkmcnt(2)
	v_mfma_f32_16x16x32_bf16 v[22:25], v[26:29], v[8:11], v[22:25]
	ds_read_b128 v[26:29], v17 offset:6400
	s_ashr_i32 s7, s6, 31
	s_add_i32 s2, s1, s0
	s_waitcnt lgkmcnt(2)
	v_mfma_f32_16x16x32_bf16 v[22:25], v[30:33], v[4:7], v[22:25]
	ds_read_b128 v[30:33], v17 offset:6464
	s_lshl_b64 s[0:1], s[6:7], 2
	v_readlane_b32 s6, v254, 41
	s_add_u32 s0, s6, s0
	v_readlane_b32 s6, v254, 43
	v_lshrrev_b32_e32 v19, 2, v74
	s_addc_u32 s1, s6, s1
	v_lshlrev_b32_e32 v72, 2, v18
	v_and_b32_e32 v20, 12, v19
	v_lshl_add_u64 v[18:19], s[0:1], 0, v[72:73]
	s_waitcnt lgkmcnt(2)
	v_mfma_f32_16x16x32_bf16 v[22:25], v[34:37], v[0:3], v[22:25]
	s_lshl_b32 s0, s2, 6
	v_or_b32_e32 v72, s0, v20
	v_lshlrev_b64 v[38:39], 9, v[72:73]
	s_waitcnt lgkmcnt(1)
	v_mfma_f32_16x16x32_bf16 v[26:29], v[26:29], v[12:15], 0
	ds_read_b128 v[34:37], v17 offset:6528
	v_lshl_add_u64 v[42:43], v[18:19], 0, v[38:39]
	ds_read_b128 v[38:41], v17 offset:6592
	global_store_dword v[42:43], v22, off
	global_store_dword v[42:43], v23, off offset:512
	s_waitcnt lgkmcnt(2)
	v_mfma_f32_16x16x32_bf16 v[26:29], v[30:33], v[8:11], v[26:29]
	ds_read_b128 v[30:33], v17 offset:10752
	global_store_dword v[42:43], v24, off offset:1024
	global_store_dword v[42:43], v25, off offset:1536
	ds_read_b128 v[22:25], v17 offset:10816
	s_waitcnt lgkmcnt(3)
	v_mfma_f32_16x16x32_bf16 v[26:29], v[34:37], v[4:7], v[26:29]
	ds_read_b128 v[34:37], v17 offset:10880
	v_or_b32_e32 v21, 48, v166
	v_mad_u32_u24 v21, v21, s92, v16
	s_waitcnt lgkmcnt(2)
	v_mfma_f32_16x16x32_bf16 v[30:33], v[30:33], v[12:15], 0
	s_add_i32 s1, s0, 64
	s_addk_i32 s0, 0x80
	v_mfma_f32_16x16x32_bf16 v[26:29], v[38:41], v[0:3], v[26:29]
	v_or_b32_e32 v38, 16, v72
	v_mov_b32_e32 v39, v73
	v_lshlrev_b64 v[38:39], 9, v[38:39]
	v_lshl_add_u64 v[42:43], v[18:19], 0, v[38:39]
	ds_read_b128 v[38:41], v17 offset:10944
	s_waitcnt lgkmcnt(2)
	v_mfma_f32_16x16x32_bf16 v[22:25], v[22:25], v[8:11], v[30:33]
	s_nop 2
	ds_read_b128 v[30:33], v21 offset:2048
	global_store_dword v[42:43], v26, off
	global_store_dword v[42:43], v27, off offset:512
	s_waitcnt lgkmcnt(2)
	v_mfma_f32_16x16x32_bf16 v[22:25], v[34:37], v[4:7], v[22:25]
	ds_read_b128 v[34:37], v21 offset:2112
	global_store_dword v[42:43], v28, off offset:1024
	global_store_dword v[42:43], v29, off offset:1536
	ds_read_b128 v[26:29], v21 offset:2176
	s_waitcnt lgkmcnt(2)
	v_mfma_f32_16x16x32_bf16 v[30:33], v[30:33], v[12:15], 0
	v_or_b32_e32 v42, 32, v72
	v_mov_b32_e32 v43, v73
	v_or_b32_e32 v72, 48, v72
	v_mfma_f32_16x16x32_bf16 v[22:25], v[38:41], v[0:3], v[22:25]
	ds_read_b128 v[38:41], v21 offset:2240
	s_waitcnt lgkmcnt(2)
	v_mfma_f32_16x16x32_bf16 v[30:33], v[34:37], v[8:11], v[30:33]
	v_lshlrev_b64 v[34:35], 9, v[42:43]
	v_lshl_add_u64 v[42:43], v[18:19], 0, v[34:35]
	ds_read_b128 v[34:37], v17 offset:19456
	s_nop 1
	global_store_dword v[42:43], v22, off
	global_store_dword v[42:43], v23, off offset:512
	s_waitcnt lgkmcnt(2)
	v_mfma_f32_16x16x32_bf16 v[26:29], v[26:29], v[4:7], v[30:33]
	v_or_b32_e32 v21, 0x70, v166
	v_mad_u32_u24 v21, v21, s92, v16
	s_nop 0
	ds_read_b128 v[30:33], v17 offset:19520
	global_store_dword v[42:43], v24, off offset:1024
	global_store_dword v[42:43], v25, off offset:1536
	ds_read_b128 v[22:25], v17 offset:19584
	s_waitcnt lgkmcnt(2)
	v_mfma_f32_16x16x32_bf16 v[34:37], v[34:37], v[12:15], 0
	v_lshlrev_b64 v[42:43], 9, v[72:73]
	v_lshl_add_u64 v[42:43], v[18:19], 0, v[42:43]
	v_or_b32_e32 v72, s1, v20
	v_mfma_f32_16x16x32_bf16 v[26:29], v[38:41], v[0:3], v[26:29]
	ds_read_b128 v[38:41], v17 offset:19648
	s_waitcnt lgkmcnt(2)
	v_mfma_f32_16x16x32_bf16 v[30:33], v[30:33], v[8:11], v[34:37]
	s_nop 2
	ds_read_b128 v[34:37], v17 offset:23808
	s_nop 0
	global_store_dword v[42:43], v26, off
	global_store_dword v[42:43], v27, off offset:512
	global_store_dword v[42:43], v28, off offset:1024
	s_waitcnt lgkmcnt(2)
	v_mfma_f32_16x16x32_bf16 v[22:25], v[22:25], v[4:7], v[30:33]
	global_store_dword v[42:43], v29, off offset:1536
	ds_read_b128 v[26:29], v17 offset:23936
	v_lshlrev_b64 v[42:43], 9, v[72:73]
	ds_read_b128 v[30:33], v17 offset:23872
	s_waitcnt lgkmcnt(2)
	v_mfma_f32_16x16x32_bf16 v[34:37], v[34:37], v[12:15], 0
	v_mfma_f32_16x16x32_bf16 v[22:25], v[38:41], v[0:3], v[22:25]
	ds_read_b128 v[38:41], v17 offset:24000
	s_waitcnt lgkmcnt(1)
	v_mfma_f32_16x16x32_bf16 v[30:33], v[30:33], v[8:11], v[34:37]
	s_nop 3
	v_lshl_add_u64 v[34:35], v[18:19], 0, v[42:43]
	global_store_dword v[34:35], v22, off
	global_store_dword v[34:35], v23, off offset:512
	v_mfma_f32_16x16x32_bf16 v[26:29], v[26:29], v[4:7], v[30:33]
	s_nop 2
	ds_read_b128 v[30:33], v17 offset:28160
	global_store_dword v[34:35], v24, off offset:1024
	global_store_dword v[34:35], v25, off offset:1536
	s_waitcnt lgkmcnt(1)
	v_mfma_f32_16x16x32_bf16 v[22:25], v[38:41], v[0:3], v[26:29]
	v_or_b32_e32 v34, 16, v72
	v_mov_b32_e32 v35, v73
	v_lshlrev_b64 v[38:39], 9, v[34:35]
	ds_read_b128 v[26:29], v17 offset:28224
	ds_read_b128 v[34:37], v17 offset:28288
	s_waitcnt lgkmcnt(2)
	v_mfma_f32_16x16x32_bf16 v[30:33], v[30:33], v[12:15], 0
	v_lshl_add_u64 v[42:43], v[18:19], 0, v[38:39]
	ds_read_b128 v[38:41], v17 offset:28352
	global_store_dword v[42:43], v22, off
	s_waitcnt lgkmcnt(2)
	v_mfma_f32_16x16x32_bf16 v[26:29], v[26:29], v[8:11], v[30:33]
	s_nop 2
	ds_read_b128 v[30:33], v21 offset:2048
	global_store_dword v[42:43], v23, off offset:512
	global_store_dword v[42:43], v24, off offset:1024
	s_waitcnt lgkmcnt(2)
	v_mfma_f32_16x16x32_bf16 v[26:29], v[34:37], v[4:7], v[26:29]
	ds_read_b128 v[34:37], v21 offset:2112
	global_store_dword v[42:43], v25, off offset:1536
	ds_read_b128 v[22:25], v21 offset:2176
	s_waitcnt lgkmcnt(2)
	v_mfma_f32_16x16x32_bf16 v[30:33], v[30:33], v[12:15], 0
	v_mfma_f32_16x16x32_bf16 v[26:29], v[38:41], v[0:3], v[26:29]
	v_or_b32_e32 v38, 32, v72
	v_mov_b32_e32 v39, v73
	v_lshlrev_b64 v[42:43], 9, v[38:39]
	ds_read_b128 v[38:41], v21 offset:2240
	s_waitcnt lgkmcnt(2)
	v_mfma_f32_16x16x32_bf16 v[30:33], v[34:37], v[8:11], v[30:33]
	ds_read_b128 v[34:37], v17 offset:36864
	v_lshl_add_u64 v[42:43], v[18:19], 0, v[42:43]
	global_store_dword v[42:43], v26, off
	global_store_dword v[42:43], v27, off offset:512
	global_store_dword v[42:43], v28, off offset:1024
	s_waitcnt lgkmcnt(2)
	v_mfma_f32_16x16x32_bf16 v[22:25], v[22:25], v[4:7], v[30:33]
	global_store_dword v[42:43], v29, off offset:1536
	ds_read_b128 v[26:29], v17 offset:36992
	v_or_b32_e32 v72, 48, v72
	ds_read_b128 v[30:33], v17 offset:36928
	s_waitcnt lgkmcnt(3)
	v_mfma_f32_16x16x32_bf16 v[22:25], v[38:41], v[0:3], v[22:25]
	v_lshlrev_b64 v[38:39], 9, v[72:73]
	v_lshl_add_u64 v[42:43], v[18:19], 0, v[38:39]
	ds_read_b128 v[38:41], v17 offset:37056
	s_waitcnt lgkmcnt(3)
	v_mfma_f32_16x16x32_bf16 v[34:37], v[34:37], v[12:15], 0
	s_nop 2
	global_store_dword v[42:43], v22, off
	global_store_dword v[42:43], v23, off offset:512
	v_or_b32_e32 v72, s0, v20
	v_lshlrev_b64 v[20:21], 9, v[72:73]
	s_waitcnt lgkmcnt(1)
	v_mfma_f32_16x16x32_bf16 v[30:33], v[30:33], v[8:11], v[34:37]
	s_nop 2
	ds_read_b128 v[34:37], v17 offset:41216
	global_store_dword v[42:43], v24, off offset:1024
	global_store_dword v[42:43], v25, off offset:1536
	v_mfma_f32_16x16x32_bf16 v[26:29], v[26:29], v[4:7], v[30:33]
	ds_read_b128 v[22:25], v17 offset:41280
	v_lshl_add_u64 v[42:43], v[18:19], 0, v[20:21]
	s_waitcnt lgkmcnt(2)
	v_mfma_f32_16x16x32_bf16 v[26:29], v[38:41], v[0:3], v[26:29]
	ds_read_b128 v[30:33], v17 offset:41344
	ds_read_b128 v[38:41], v17 offset:41408
	s_nop 5
	global_store_dword v[42:43], v26, off
	global_store_dword v[42:43], v27, off offset:512
	s_waitcnt lgkmcnt(3)
	v_mfma_f32_16x16x32_bf16 v[34:37], v[34:37], v[12:15], 0
	s_waitcnt lgkmcnt(2)
	v_mfma_f32_16x16x32_bf16 v[20:23], v[22:25], v[8:11], v[34:37]
	ds_read_b128 v[24:27], v17 offset:45568
	global_store_dword v[42:43], v28, off offset:1024
	global_store_dword v[42:43], v29, off offset:1536
	s_nop 2
	v_or_b32_e32 v36, 16, v72
	s_waitcnt lgkmcnt(2)
	v_mfma_f32_16x16x32_bf16 v[20:23], v[30:33], v[4:7], v[20:23]
	ds_read_b128 v[28:31], v17 offset:45632
	ds_read_b128 v[32:35], v17 offset:45696
	v_mov_b32_e32 v37, v73
	s_waitcnt lgkmcnt(2)
	v_mfma_f32_16x16x32_bf16 v[24:27], v[24:27], v[12:15], 0
	v_lshlrev_b64 v[36:37], 9, v[36:37]
	v_mfma_f32_16x16x32_bf16 v[20:23], v[38:41], v[0:3], v[20:23]
	v_lshl_add_u64 v[40:41], v[18:19], 0, v[36:37]
	ds_read_b128 v[36:39], v17 offset:45760
	v_or_b32_e32 v17, 0xb0, v166
	v_mad_u32_u24 v42, v17, s92, v16
	s_waitcnt lgkmcnt(2)
	v_mfma_f32_16x16x32_bf16 v[24:27], v[28:31], v[8:11], v[24:27]
	ds_read_b128 v[28:31], v42 offset:2048
	s_nop 0
	global_store_dword v[40:41], v20, off
	global_store_dword v[40:41], v21, off offset:512
	v_or_b32_e32 v16, 32, v72
	s_waitcnt lgkmcnt(2)
	v_mfma_f32_16x16x32_bf16 v[24:27], v[32:35], v[4:7], v[24:27]
	ds_read_b128 v[32:35], v42 offset:2112
	global_store_dword v[40:41], v22, off offset:1024
	global_store_dword v[40:41], v23, off offset:1536
	ds_read_b128 v[20:23], v42 offset:2176
	s_waitcnt lgkmcnt(2)
	v_mfma_f32_16x16x32_bf16 v[12:15], v[28:31], v[12:15], 0
	ds_read_b128 v[28:31], v42 offset:2240
	v_mov_b32_e32 v17, v73
	v_or_b32_e32 v72, 48, v72
	s_waitcnt lgkmcnt(2)
	v_mfma_f32_16x16x32_bf16 v[8:11], v[32:35], v[8:11], v[12:15]
	s_waitcnt lgkmcnt(1)
	v_mfma_f32_16x16x32_bf16 v[4:7], v[20:23], v[4:7], v[8:11]
	s_nop 0
	v_lshlrev_b64 v[12:13], 9, v[16:17]
	v_lshl_add_u64 v[12:13], v[18:19], 0, v[12:13]
	v_mfma_f32_16x16x32_bf16 v[24:27], v[36:39], v[0:3], v[24:27]
	s_waitcnt lgkmcnt(0)
	v_mfma_f32_16x16x32_bf16 v[0:3], v[28:31], v[0:3], v[4:7]
	s_nop 2
	v_lshlrev_b64 v[4:5], 9, v[72:73]
	v_lshl_add_u64 v[4:5], v[18:19], 0, v[4:5]
	s_nop 0
	global_store_dword v[12:13], v24, off
	global_store_dword v[12:13], v25, off offset:512
	global_store_dword v[12:13], v26, off offset:1024
	global_store_dword v[12:13], v27, off offset:1536
	global_store_dword v[4:5], v0, off
	global_store_dword v[4:5], v1, off offset:512
	global_store_dword v[4:5], v2, off offset:1024
	global_store_dword v[4:5], v3, off offset:1536
	s_cbranch_execz .LBB0_647

.LBB0_755:
	v_ashrrev_i32_e32 v8, 11, v7
	v_mul_hi_i32 v0, v8, s1
	v_lshrrev_b32_e32 v1, 31, v0
	v_lshrrev_b32_e32 v0, 1, v0
	v_add_u32_e32 v0, v0, v1
	v_lshlrev_b32_e32 v1, 2, v7
	v_and_b32_e32 v12, 0x1f80, v1
	v_mad_u64_u32 v[10:11], s[18:19], v0, s2, v[8:9]
	v_or_b32_e32 v4, v12, v6
	v_mov_b32_e32 v0, 0
	v_mov_b32_e32 v1, v5
	v_mov_b32_e32 v2, 0
	v_mov_b32_e32 v3, v5
	v_lshlrev_b32_e32 v14, 13, v10
	v_or_b32_e32 v14, v14, v4
	v_lshlrev_b32_e32 v15, 2, v14
	v_lshlrev_b32_e32 v16, 1, v14
	v_mbcnt_lo_u32_b32 v17, -1, 0
	v_mbcnt_hi_u32_b32 v17, -1, v17
	v_and_b32_e32 v17, 31, v17
	v_mul_u32_u24_e32 v17, 12, v17
	v_add_lshl_u32 v17, v17, v10, 2
	global_load_dword v18, v17, s[10:11]
	global_load_dwordx4 v[120:123], v15, s[8:9] nt
	v_add_u32_e32 v15, 0x60000, v15
	global_load_dwordx4 v[124:127], v15, s[8:9] nt
	v_add_u32_e32 v15, 0x60000, v15
	global_load_dwordx4 v[128:131], v15, s[8:9] nt
	v_add_u32_e32 v15, 0x60000, v15
	global_load_dwordx4 v[132:135], v15, s[8:9] nt
	v_add_u32_e32 v15, 0x60000, v15
	global_load_dwordx4 v[136:139], v15, s[8:9] nt
	v_add_u32_e32 v15, 0x60000, v15
	global_load_dwordx4 v[140:143], v15, s[8:9] nt
	v_add_u32_e32 v15, 0x60000, v15
	global_load_dwordx4 v[144:147], v15, s[8:9] nt
	v_add_u32_e32 v15, 0x60000, v15
	global_load_dwordx4 v[148:151], v15, s[8:9] nt
	v_add_u32_e32 v15, 0x60000, v15
	global_load_dwordx4 v[152:155], v15, s[8:9] nt
	v_add_u32_e32 v15, 0x60000, v15
	global_load_dwordx4 v[156:159], v15, s[8:9] nt
	v_add_u32_e32 v15, 0x60000, v15
	global_load_dwordx4 v[160:163], v15, s[8:9] nt
	v_add_u32_e32 v15, 0x60000, v15
	global_load_dwordx4 v[164:167], v15, s[8:9] nt
	v_add_u32_e32 v15, 0x60000, v15
	global_load_dwordx4 v[168:171], v15, s[8:9] nt
	v_add_u32_e32 v15, 0x60000, v15
	global_load_dwordx4 v[172:175], v15, s[8:9] nt
	v_add_u32_e32 v15, 0x60000, v15
	global_load_dwordx4 v[176:179], v15, s[8:9] nt
	v_add_u32_e32 v15, 0x60000, v15
	global_load_dwordx4 v[180:183], v15, s[8:9] nt
	v_add_u32_e32 v15, 0x60000, v15
	global_load_dwordx4 v[184:187], v15, s[8:9] nt
	v_add_u32_e32 v15, 0x60000, v15
	global_load_dwordx4 v[196:199], v15, s[8:9] nt
	v_add_u32_e32 v15, 0x60000, v15
	global_load_dwordx4 v[200:203], v15, s[8:9] nt
	v_add_u32_e32 v15, 0x60000, v15
	global_load_dwordx4 v[204:207], v15, s[8:9] nt
	v_add_u32_e32 v15, 0x60000, v15
	global_load_dwordx4 v[208:211], v15, s[8:9] nt
	v_add_u32_e32 v15, 0x60000, v15
	global_load_dwordx4 v[212:215], v15, s[8:9] nt
	v_add_u32_e32 v15, 0x60000, v15
	global_load_dwordx4 v[216:219], v15, s[8:9] nt
	v_add_u32_e32 v15, 0x60000, v15
	global_load_dwordx4 v[220:223], v15, s[8:9] nt
	v_add_u32_e32 v15, 0x60000, v15
	global_load_dwordx4 v[224:227], v15, s[8:9] nt
	v_add_u32_e32 v15, 0x60000, v15
	global_load_dwordx4 v[228:231], v15, s[8:9] nt
	v_add_u32_e32 v15, 0x60000, v15
	global_load_dwordx4 v[232:235], v15, s[8:9] nt
	v_add_u32_e32 v15, 0x60000, v15
	global_load_dwordx4 v[236:239], v15, s[8:9] nt
	v_add_u32_e32 v15, 0x60000, v15
	global_load_dwordx4 v[240:243], v15, s[8:9] nt
	v_add_u32_e32 v15, 0x60000, v15
	global_load_dwordx4 v[244:247], v15, s[8:9] nt
	v_add_u32_e32 v15, 0x60000, v15
	global_load_dwordx4 v[248:251], v15, s[8:9] nt
	v_add_u32_e32 v15, 0x60000, v15
	global_load_dwordx4 v[60:63], v15, s[8:9] nt
	v_cvt_pk_bf16_f32 v20, v0, v1
	v_cvt_pk_bf16_f32 v21, v2, v3
	global_store_dwordx2 v16, v[20:21], s[12:13]
	v_add_u32_e32 v16, 0x30000, v16
	s_waitcnt vmcnt(32)
	v_readlane_b32 s18, v18, 0
	s_nop 1
	v_fma_f32 v0, v0, s18, v120
	v_fma_f32 v1, v1, s18, v121
	v_fma_f32 v2, v2, s18, v122
	v_fma_f32 v3, v3, s18, v123
	v_cvt_pk_bf16_f32 v22, v0, v1
	v_cvt_pk_bf16_f32 v23, v2, v3
	global_store_dwordx2 v16, v[22:23], s[12:13]
	v_add_u32_e32 v16, 0x30000, v16
	s_waitcnt vmcnt(32)
	v_readlane_b32 s18, v18, 1
	s_nop 1
	v_fma_f32 v0, v0, s18, v124
	v_fma_f32 v1, v1, s18, v125
	v_fma_f32 v2, v2, s18, v126
	v_fma_f32 v3, v3, s18, v127
	v_cvt_pk_bf16_f32 v20, v0, v1
	v_cvt_pk_bf16_f32 v21, v2, v3
	global_store_dwordx2 v16, v[20:21], s[12:13]
	v_add_u32_e32 v16, 0x30000, v16
	s_waitcnt vmcnt(32)
	v_readlane_b32 s18, v18, 2
	s_nop 1
	v_fma_f32 v0, v0, s18, v128
	v_fma_f32 v1, v1, s18, v129
	v_fma_f32 v2, v2, s18, v130
	v_fma_f32 v3, v3, s18, v131
	v_cvt_pk_bf16_f32 v22, v0, v1
	v_cvt_pk_bf16_f32 v23, v2, v3
	global_store_dwordx2 v16, v[22:23], s[12:13]
	v_add_u32_e32 v16, 0x30000, v16
	s_waitcnt vmcnt(32)
	v_readlane_b32 s18, v18, 3
	s_nop 1
	v_fma_f32 v0, v0, s18, v132
	v_fma_f32 v1, v1, s18, v133
	v_fma_f32 v2, v2, s18, v134
	v_fma_f32 v3, v3, s18, v135
	v_cvt_pk_bf16_f32 v20, v0, v1
	v_cvt_pk_bf16_f32 v21, v2, v3
	global_store_dwordx2 v16, v[20:21], s[12:13]
	v_add_u32_e32 v16, 0x30000, v16
	s_waitcnt vmcnt(32)
	v_readlane_b32 s18, v18, 4
	s_nop 1
	v_fma_f32 v0, v0, s18, v136
	v_fma_f32 v1, v1, s18, v137
	v_fma_f32 v2, v2, s18, v138
	v_fma_f32 v3, v3, s18, v139
	v_cvt_pk_bf16_f32 v22, v0, v1
	v_cvt_pk_bf16_f32 v23, v2, v3
	global_store_dwordx2 v16, v[22:23], s[12:13]
	v_add_u32_e32 v16, 0x30000, v16
	s_waitcnt vmcnt(32)
	v_readlane_b32 s18, v18, 5
	s_nop 1
	v_fma_f32 v0, v0, s18, v140
	v_fma_f32 v1, v1, s18, v141
	v_fma_f32 v2, v2, s18, v142
	v_fma_f32 v3, v3, s18, v143
	v_cvt_pk_bf16_f32 v20, v0, v1
	v_cvt_pk_bf16_f32 v21, v2, v3
	global_store_dwordx2 v16, v[20:21], s[12:13]
	v_add_u32_e32 v16, 0x30000, v16
	s_waitcnt vmcnt(32)
	v_readlane_b32 s18, v18, 6
	s_nop 1
	v_fma_f32 v0, v0, s18, v144
	v_fma_f32 v1, v1, s18, v145
	v_fma_f32 v2, v2, s18, v146
	v_fma_f32 v3, v3, s18, v147
	v_cvt_pk_bf16_f32 v22, v0, v1
	v_cvt_pk_bf16_f32 v23, v2, v3
	global_store_dwordx2 v16, v[22:23], s[12:13]
	v_add_u32_e32 v16, 0x30000, v16
	s_waitcnt vmcnt(32)
	v_readlane_b32 s18, v18, 7
	s_nop 1
	v_fma_f32 v0, v0, s18, v148
	v_fma_f32 v1, v1, s18, v149
	v_fma_f32 v2, v2, s18, v150
	v_fma_f32 v3, v3, s18, v151
	v_cvt_pk_bf16_f32 v20, v0, v1
	v_cvt_pk_bf16_f32 v21, v2, v3
	global_store_dwordx2 v16, v[20:21], s[12:13]
	v_add_u32_e32 v16, 0x30000, v16
	s_waitcnt vmcnt(32)
	v_readlane_b32 s18, v18, 8
	s_nop 1
	v_fma_f32 v0, v0, s18, v152
	v_fma_f32 v1, v1, s18, v153
	v_fma_f32 v2, v2, s18, v154
	v_fma_f32 v3, v3, s18, v155
	v_cvt_pk_bf16_f32 v22, v0, v1
	v_cvt_pk_bf16_f32 v23, v2, v3
	global_store_dwordx2 v16, v[22:23], s[12:13]
	v_add_u32_e32 v16, 0x30000, v16
	s_waitcnt vmcnt(32)
	v_readlane_b32 s18, v18, 9
	s_nop 1
	v_fma_f32 v0, v0, s18, v156
	v_fma_f32 v1, v1, s18, v157
	v_fma_f32 v2, v2, s18, v158
	v_fma_f32 v3, v3, s18, v159
	v_cvt_pk_bf16_f32 v20, v0, v1
	v_cvt_pk_bf16_f32 v21, v2, v3
	global_store_dwordx2 v16, v[20:21], s[12:13]
	v_add_u32_e32 v16, 0x30000, v16
	s_waitcnt vmcnt(32)
	v_readlane_b32 s18, v18, 10
	s_nop 1
	v_fma_f32 v0, v0, s18, v160
	v_fma_f32 v1, v1, s18, v161
	v_fma_f32 v2, v2, s18, v162
	v_fma_f32 v3, v3, s18, v163
	v_cvt_pk_bf16_f32 v22, v0, v1
	v_cvt_pk_bf16_f32 v23, v2, v3
	global_store_dwordx2 v16, v[22:23], s[12:13]
	v_add_u32_e32 v16, 0x30000, v16
	s_waitcnt vmcnt(32)
	v_readlane_b32 s18, v18, 11
	s_nop 1
	v_fma_f32 v0, v0, s18, v164
	v_fma_f32 v1, v1, s18, v165
	v_fma_f32 v2, v2, s18, v166
	v_fma_f32 v3, v3, s18, v167
	v_cvt_pk_bf16_f32 v20, v0, v1
	v_cvt_pk_bf16_f32 v21, v2, v3
	global_store_dwordx2 v16, v[20:21], s[12:13]
	v_add_u32_e32 v16, 0x30000, v16
	s_waitcnt vmcnt(32)
	v_readlane_b32 s18, v18, 12
	s_nop 1
	v_fma_f32 v0, v0, s18, v168
	v_fma_f32 v1, v1, s18, v169
	v_fma_f32 v2, v2, s18, v170
	v_fma_f32 v3, v3, s18, v171
	v_cvt_pk_bf16_f32 v22, v0, v1
	v_cvt_pk_bf16_f32 v23, v2, v3
	global_store_dwordx2 v16, v[22:23], s[12:13]
	v_add_u32_e32 v16, 0x30000, v16
	s_waitcnt vmcnt(32)
	v_readlane_b32 s18, v18, 13
	s_nop 1
	v_fma_f32 v0, v0, s18, v172
	v_fma_f32 v1, v1, s18, v173
	v_fma_f32 v2, v2, s18, v174
	v_fma_f32 v3, v3, s18, v175
	v_cvt_pk_bf16_f32 v20, v0, v1
	v_cvt_pk_bf16_f32 v21, v2, v3
	global_store_dwordx2 v16, v[20:21], s[12:13]
	v_add_u32_e32 v16, 0x30000, v16
	s_waitcnt vmcnt(32)
	v_readlane_b32 s18, v18, 14
	s_nop 1
	v_fma_f32 v0, v0, s18, v176
	v_fma_f32 v1, v1, s18, v177
	v_fma_f32 v2, v2, s18, v178
	v_fma_f32 v3, v3, s18, v179
	v_cvt_pk_bf16_f32 v22, v0, v1
	v_cvt_pk_bf16_f32 v23, v2, v3
	global_store_dwordx2 v16, v[22:23], s[12:13]
	v_add_u32_e32 v16, 0x30000, v16
	s_waitcnt vmcnt(32)
	v_readlane_b32 s18, v18, 15
	s_nop 1
	v_fma_f32 v0, v0, s18, v180
	v_fma_f32 v1, v1, s18, v181
	v_fma_f32 v2, v2, s18, v182
	v_fma_f32 v3, v3, s18, v183
	v_cvt_pk_bf16_f32 v20, v0, v1
	v_cvt_pk_bf16_f32 v21, v2, v3
	global_store_dwordx2 v16, v[20:21], s[12:13]
	v_add_u32_e32 v16, 0x30000, v16
	s_waitcnt vmcnt(32)
	v_readlane_b32 s18, v18, 16
	s_nop 1
	v_fma_f32 v0, v0, s18, v184
	v_fma_f32 v1, v1, s18, v185
	v_fma_f32 v2, v2, s18, v186
	v_fma_f32 v3, v3, s18, v187
	v_cvt_pk_bf16_f32 v22, v0, v1
	v_cvt_pk_bf16_f32 v23, v2, v3
	global_store_dwordx2 v16, v[22:23], s[12:13]
	v_add_u32_e32 v16, 0x30000, v16
	s_waitcnt vmcnt(32)
	v_readlane_b32 s18, v18, 17
	s_nop 1
	v_fma_f32 v0, v0, s18, v196
	v_fma_f32 v1, v1, s18, v197
	v_fma_f32 v2, v2, s18, v198
	v_fma_f32 v3, v3, s18, v199
	v_cvt_pk_bf16_f32 v20, v0, v1
	v_cvt_pk_bf16_f32 v21, v2, v3
	global_store_dwordx2 v16, v[20:21], s[12:13]
	v_add_u32_e32 v16, 0x30000, v16
	s_waitcnt vmcnt(32)
	v_readlane_b32 s18, v18, 18
	s_nop 1
	v_fma_f32 v0, v0, s18, v200
	v_fma_f32 v1, v1, s18, v201
	v_fma_f32 v2, v2, s18, v202
	v_fma_f32 v3, v3, s18, v203
	v_cvt_pk_bf16_f32 v22, v0, v1
	v_cvt_pk_bf16_f32 v23, v2, v3
	global_store_dwordx2 v16, v[22:23], s[12:13]
	v_add_u32_e32 v16, 0x30000, v16
	s_waitcnt vmcnt(32)
	v_readlane_b32 s18, v18, 19
	s_nop 1
	v_fma_f32 v0, v0, s18, v204
	v_fma_f32 v1, v1, s18, v205
	v_fma_f32 v2, v2, s18, v206
	v_fma_f32 v3, v3, s18, v207
	v_cvt_pk_bf16_f32 v20, v0, v1
	v_cvt_pk_bf16_f32 v21, v2, v3
	global_store_dwordx2 v16, v[20:21], s[12:13]
	v_add_u32_e32 v16, 0x30000, v16
	s_waitcnt vmcnt(32)
	v_readlane_b32 s18, v18, 20
	s_nop 1
	v_fma_f32 v0, v0, s18, v208
	v_fma_f32 v1, v1, s18, v209
	v_fma_f32 v2, v2, s18, v210
	v_fma_f32 v3, v3, s18, v211
	v_cvt_pk_bf16_f32 v22, v0, v1
	v_cvt_pk_bf16_f32 v23, v2, v3
	global_store_dwordx2 v16, v[22:23], s[12:13]
	v_add_u32_e32 v16, 0x30000, v16
	s_waitcnt vmcnt(32)
	v_readlane_b32 s18, v18, 21
	s_nop 1
	v_fma_f32 v0, v0, s18, v212
	v_fma_f32 v1, v1, s18, v213
	v_fma_f32 v2, v2, s18, v214
	v_fma_f32 v3, v3, s18, v215
	v_cvt_pk_bf16_f32 v20, v0, v1
	v_cvt_pk_bf16_f32 v21, v2, v3
	global_store_dwordx2 v16, v[20:21], s[12:13]
	v_add_u32_e32 v16, 0x30000, v16
	s_waitcnt vmcnt(32)
	v_readlane_b32 s18, v18, 22
	s_nop 1
	v_fma_f32 v0, v0, s18, v216
	v_fma_f32 v1, v1, s18, v217
	v_fma_f32 v2, v2, s18, v218
	v_fma_f32 v3, v3, s18, v219
	v_cvt_pk_bf16_f32 v22, v0, v1
	v_cvt_pk_bf16_f32 v23, v2, v3
	global_store_dwordx2 v16, v[22:23], s[12:13]
	v_add_u32_e32 v16, 0x30000, v16
	s_waitcnt vmcnt(32)
	v_readlane_b32 s18, v18, 23
	s_nop 1
	v_fma_f32 v0, v0, s18, v220
	v_fma_f32 v1, v1, s18, v221
	v_fma_f32 v2, v2, s18, v222
	v_fma_f32 v3, v3, s18, v223
	v_cvt_pk_bf16_f32 v20, v0, v1
	v_cvt_pk_bf16_f32 v21, v2, v3
	global_store_dwordx2 v16, v[20:21], s[12:13]
	v_add_u32_e32 v16, 0x30000, v16
	s_waitcnt vmcnt(32)
	v_readlane_b32 s18, v18, 24
	s_nop 1
	v_fma_f32 v0, v0, s18, v224
	v_fma_f32 v1, v1, s18, v225
	v_fma_f32 v2, v2, s18, v226
	v_fma_f32 v3, v3, s18, v227
	v_cvt_pk_bf16_f32 v22, v0, v1
	v_cvt_pk_bf16_f32 v23, v2, v3
	global_store_dwordx2 v16, v[22:23], s[12:13]
	v_add_u32_e32 v16, 0x30000, v16
	s_waitcnt vmcnt(32)
	v_readlane_b32 s18, v18, 25
	s_nop 1
	v_fma_f32 v0, v0, s18, v228
	v_fma_f32 v1, v1, s18, v229
	v_fma_f32 v2, v2, s18, v230
	v_fma_f32 v3, v3, s18, v231
	v_cvt_pk_bf16_f32 v20, v0, v1
	v_cvt_pk_bf16_f32 v21, v2, v3
	global_store_dwordx2 v16, v[20:21], s[12:13]
	v_add_u32_e32 v16, 0x30000, v16
	s_waitcnt vmcnt(32)
	v_readlane_b32 s18, v18, 26
	s_nop 1
	v_fma_f32 v0, v0, s18, v232
	v_fma_f32 v1, v1, s18, v233
	v_fma_f32 v2, v2, s18, v234
	v_fma_f32 v3, v3, s18, v235
	v_cvt_pk_bf16_f32 v22, v0, v1
	v_cvt_pk_bf16_f32 v23, v2, v3
	global_store_dwordx2 v16, v[22:23], s[12:13]
	v_add_u32_e32 v16, 0x30000, v16
	s_waitcnt vmcnt(32)
	v_readlane_b32 s18, v18, 27
	s_nop 1
	v_fma_f32 v0, v0, s18, v236
	v_fma_f32 v1, v1, s18, v237
	v_fma_f32 v2, v2, s18, v238
	v_fma_f32 v3, v3, s18, v239
	v_cvt_pk_bf16_f32 v20, v0, v1
	v_cvt_pk_bf16_f32 v21, v2, v3
	global_store_dwordx2 v16, v[20:21], s[12:13]
	v_add_u32_e32 v16, 0x30000, v16
	s_waitcnt vmcnt(32)
	v_readlane_b32 s18, v18, 28
	s_nop 1
	v_fma_f32 v0, v0, s18, v240
	v_fma_f32 v1, v1, s18, v241
	v_fma_f32 v2, v2, s18, v242
	v_fma_f32 v3, v3, s18, v243
	v_cvt_pk_bf16_f32 v22, v0, v1
	v_cvt_pk_bf16_f32 v23, v2, v3
	global_store_dwordx2 v16, v[22:23], s[12:13]
	v_add_u32_e32 v16, 0x30000, v16
	s_waitcnt vmcnt(32)
	v_readlane_b32 s18, v18, 29
	s_nop 1
	v_fma_f32 v0, v0, s18, v244
	v_fma_f32 v1, v1, s18, v245
	v_fma_f32 v2, v2, s18, v246
	v_fma_f32 v3, v3, s18, v247
	v_cvt_pk_bf16_f32 v20, v0, v1
	v_cvt_pk_bf16_f32 v21, v2, v3
	global_store_dwordx2 v16, v[20:21], s[12:13]
	v_add_u32_e32 v16, 0x30000, v16
	s_waitcnt vmcnt(32)
	v_readlane_b32 s18, v18, 30
	s_nop 1
	v_fma_f32 v0, v0, s18, v248
	v_fma_f32 v1, v1, s18, v249
	v_fma_f32 v2, v2, s18, v250
	v_fma_f32 v3, v3, s18, v251
	v_cvt_pk_bf16_f32 v22, v0, v1
	v_cvt_pk_bf16_f32 v23, v2, v3
	global_store_dwordx2 v16, v[22:23], s[12:13]
	s_waitcnt vmcnt(32)
	v_readlane_b32 s18, v18, 31
	s_nop 1
	v_fma_f32 v0, v0, s18, v60
	v_fma_f32 v1, v1, s18, v61
	v_fma_f32 v2, v2, s18, v62
	v_fma_f32 v3, v3, s18, v63
	v_ashrrev_i32_e32 v9, 31, v8
	v_lshlrev_b64 v[8:9], 15, v[8:9]
	v_lshl_add_u64 v[8:9], s[14:15], 0, v[8:9]
	v_lshlrev_b32_e32 v4, 2, v12
	v_add_u32_e32 v7, s0, v7
	v_lshl_add_u64 v[8:9], v[8:9], 0, v[4:5]
	v_lshlrev_b32_e32 v4, 2, v6
	v_cmp_lt_i32_e32 vcc, s3, v7
	v_lshl_add_u64 v[8:9], v[8:9], 0, v[4:5]
	s_or_b64 s[16:17], vcc, s[16:17]
	global_store_dwordx4 v[8:9], v[0:3], off
	s_andn2_b64 exec, exec, s[16:17]
	s_cbranch_execnz .LBB0_755
